# one static s_setprio 1 for waves 4-7 through the attention phase (dropped before the grid sync)
# baseline (speedup 1.0000x reference)
; #define LAS __attribute__((address_space(3)))
; __global__ void __launch_bounds__(512, 2) hymba_fwd(Args A_unused) {
;     ...
;             LAS float* lut = (LAS float*)lds;
;             { const float* tab = Ap->in[1];
;               for (int e = tid; e < 4 * 1024 * 4; e += 512) { const int r = e & 3, dist = (e >> 2) & 1023, gg = e >> 12; lut[e] = tab[rel_bucket_i(dist) * 16 + gg * 4 + r]; } }
;             __syncthreads();
;             LAS float* imp = (LAS float*)(lds + 65536 + wave * 8192);
;             for (int i = 0; ; ++i) {
;                 const int unit = i * G + blk; if (unit >= 2048) break;
;                 const int bg = unit >> 8; int qt = unit & 255; qt = ((qt & 7) << 5) | (qt >> 3);
;                 if (i & 1) qt = 255 - qt;
;                 nsa_wave(Ap, l, bg >> 2, bg & 3, qt * 32 + wave * 4, lut, imp, lane);
;             }
.LBB0_890:
	s_or_b64 exec, exec, s[0:1]
	s_cmpk_gt_i32 s91, 0x7ff
	s_waitcnt lgkmcnt(0)
	s_barrier
	s_cbranch_scc1 .LBB0_1284
	s_cmp_lt_u32 s22, 4
	s_cbranch_scc1 .Lp3_prio
	s_setprio 1
.Lp3_prio:
	s_lshl_b32 s0, s22, 13
	s_add_i32 s93, s0, 0
	s_add_i32 s93, s93, 0x10000
	v_lshrrev_b32_e32 v1, 4, v89
	v_lshl_add_u32 v3, v1, 11, s93
	v_or_b32_e32 v135, 16, v128
	v_or_b32_e32 v138, 32, v128
	v_or_b32_e32 v141, 48, v89
	v_or_b32_e32 v152, 64, v128
	v_or_b32_e32 v155, 0x50, v128
	v_or_b32_e32 v158, 0x60, v128
	v_or_b32_e32 v161, 0x70, v89
	v_lshl_add_u32 v133, v128, 4, v3
	v_lshl_add_u32 v136, v135, 4, v3
	v_lshl_add_u32 v139, v138, 4, v3
	v_lshl_add_u32 v142, v141, 4, v3
	v_lshl_add_u32 v153, v152, 4, v3
	v_lshl_add_u32 v156, v155, 4, v3
	v_lshl_add_u32 v159, v158, 4, v3
	v_lshl_add_u32 v162, v161, 4, v3
	v_add_u32_e32 v3, 1, v33
	v_writelane_b32 v254, s80, 17
	v_and_or_b32 v165, v3, 15, v129
	v_add_u32_e32 v3, 2, v33
	v_writelane_b32 v254, s81, 18
	v_and_or_b32 v188, v3, 15, v129
	v_add_u32_e32 v3, 3, v33
	v_cmp_eq_u32_e64 s[18:19], 1, v128
	v_and_or_b32 v189, v3, 15, v129
	v_add_u32_e32 v3, 4, v33
	v_writelane_b32 v254, s18, 19
	s_load_dwordx2 s[94:95], s[2:3], 0xd8
	v_and_or_b32 v190, v3, 15, v129
	v_add_u32_e32 v3, 5, v33
	v_writelane_b32 v254, s19, 20
	v_cmp_eq_u32_e64 s[18:19], 2, v128
	v_and_or_b32 v191, v3, 15, v129
	v_add_u32_e32 v3, 6, v33
	v_writelane_b32 v254, s18, 21
	v_and_or_b32 v192, v3, 15, v129
	v_add_u32_e32 v3, 7, v33
	v_writelane_b32 v254, s19, 22
	v_cmp_eq_u32_e64 s[18:19], 3, v128
	v_and_or_b32 v193, v3, 15, v129
	v_add_u32_e32 v3, 9, v33
	v_writelane_b32 v254, s18, 23
	s_lshl_b32 s92, s22, 2
	v_and_or_b32 v194, v3, 15, v129
	v_add_u32_e32 v3, 10, v33
	v_writelane_b32 v254, s19, 24
	v_cmp_eq_u32_e64 s[18:19], 4, v128
	s_mov_b64 s[14:15], s[82:83]
	s_waitcnt lgkmcnt(0)
	s_add_u32 s82, s94, 0x1ba00000
	v_and_or_b32 v195, v3, 15, v129
	v_add_u32_e32 v3, 11, v33
	v_writelane_b32 v254, s18, 25
	s_addc_u32 s83, s95, 0
	v_and_or_b32 v196, v3, 15, v129
	v_add_u32_e32 v3, 12, v33
	v_writelane_b32 v254, s19, 26
	v_cmp_eq_u32_e64 s[18:19], 5, v128
	s_mov_b64 s[16:17], s[86:87]
	v_and_or_b32 v197, v3, 15, v129
	v_add_u32_e32 v3, 13, v33
	s_add_u32 s87, s94, 0x2c000000
	v_writelane_b32 v254, s18, 27
	v_and_or_b32 v198, v3, 15, v129
	v_add_u32_e32 v3, 14, v33
	s_addc_u32 s88, s95, 0
	v_writelane_b32 v254, s19, 28
	v_cmp_eq_u32_e64 s[18:19], 6, v128
	v_bfe_u32 v131, v33, 2, 2
	v_and_or_b32 v199, v3, 15, v129
	v_add_u32_e32 v3, -1, v33
	s_add_u32 s80, s94, 0x29200000
	v_writelane_b32 v254, s18, 29
	v_lshlrev_b32_e32 v0, 3, v1
	v_and_or_b32 v200, v3, 15, v129
	s_addc_u32 s81, s95, 0
	v_lshlrev_b32_e32 v88, 2, v1
	v_writelane_b32 v254, s19, 30
	v_lshlrev_b32_e32 v1, 6, v1
	v_or_b32_e32 v3, s92, v131
	v_lshlrev_b32_e32 v2, 11, v131
	v_sub_u32_e32 v1, v3, v1
	s_add_u32 s84, s94, s14
	v_writelane_b32 v254, s14, 31
	v_add_u32_e32 v202, 0xfffffcb1, v1
	v_mov_b32_e32 v85, v145
	v_writelane_b32 v254, s15, 32
	s_addc_u32 s14, s95, s15
	v_or3_b32 v1, s0, v2, v129
	s_add_u32 s15, s94, s16
	v_writelane_b32 v254, s16, 33
	v_add_u32_e32 v203, 0, v1
	v_sub_u32_e32 v1, v3, v88
	v_lshl_add_u64 v[2:3], s[94:95], 0, v[84:85]
	s_mov_b64 s[0:1], 0x2c801c00
	v_lshl_add_u32 v132, v130, 2, 0
	v_mov_b32_e32 v87, v145
	s_mov_b32 s86, 0
	v_cmp_eq_u32_e64 s[2:3], 0, v130
	v_cmp_eq_u32_e64 s[4:5], 0, v128
	v_add_u32_e32 v134, -16, v133
	v_add_u32_e32 v137, -16, v136
	v_add_u32_e32 v140, -16, v139
	v_add_u32_e32 v143, -16, v142
	v_add_u32_e32 v154, -16, v153
	v_add_u32_e32 v157, -16, v156
	v_add_u32_e32 v160, -16, v159
	v_add_u32_e32 v163, -16, v162
	v_or_b32_e32 v164, 0x100000, v128
	v_lshlrev_b32_e32 v201, 4, v131
	v_cmp_gt_u32_e64 s[6:7], 4, v128
	v_cmp_eq_u32_e64 s[8:9], 1, v131
	v_cmp_eq_u32_e64 s[10:11], 2, v131
	v_cmp_eq_u32_e64 s[12:13], 3, v131
	v_cmp_eq_u32_e64 s[26:27], 7, v128
	v_cmp_eq_u32_e64 s[28:29], 8, v128
	v_cmp_eq_u32_e64 s[30:31], 9, v128
	v_cmp_eq_u32_e64 s[34:35], 10, v128
	v_cmp_eq_u32_e64 s[36:37], 11, v128
	v_cmp_eq_u32_e64 s[38:39], 12, v128
	v_cmp_eq_u32_e64 s[40:41], 13, v128
	v_cmp_eq_u32_e64 s[42:43], 14, v128
	v_cmp_eq_u32_e64 s[44:45], 15, v128
	v_writelane_b32 v254, s17, 34
	s_addc_u32 s16, s95, s17
	v_subrev_u32_e32 v204, 51, v1
	v_lshl_add_u64 v[90:91], v[2:3], 0, s[0:1]
	v_lshlrev_b32_e32 v92, 1, v0
	v_lshlrev_b32_e32 v94, 1, v88
	s_mov_b32 s1, s91
	s_branch .LBB0_893

; __global__ void __launch_bounds__(512, 2) hymba_fwd(Args A_unused) {
;     ...
;             __syncthreads();
;         }
;         FAST_SYNC();
.LBB0_1284:
	s_setprio 0
	s_barrier
	s_waitcnt vmcnt(0) lgkmcnt(0)
	s_barrier
	v_mbcnt_lo_u32_b32 v0, -1, 0
	v_mbcnt_hi_u32_b32 v0, -1, v0
	s_nop 0
	v_cmp_eq_u32_e32 vcc, 0, v0
	s_and_b64 s[2:3], s[92:93], vcc
	s_and_saveexec_b64 s[0:1], s[2:3]
	s_cbranch_execz .LBB0_1298
	s_mov_b64 s[2:3], s[68:69]
	s_load_dwordx2 s[2:3], s[2:3], 0xd8
	s_mov_b64 s[4:5], exec
	buffer_wbl2 sc1
	s_waitcnt vmcnt(0) lgkmcnt(0)
	s_waitcnt vmcnt(0)
	v_mbcnt_lo_u32_b32 v0, s4, 0
	v_mbcnt_hi_u32_b32 v0, s5, v0
	v_cmp_eq_u32_e32 vcc, 0, v0
	s_and_saveexec_b64 s[6:7], vcc
	s_cbranch_execz .LBB0_1287
	s_bcnt1_i32_b64 s4, s[4:5]
	v_mov_b32_e32 v0, s4
	global_atomic_add v145, v0, s[2:3]
